# attention pass 2: removed the redundant masked-score guard (exp2 underflows to 0) = -160 VALU per unit, on top of scan store-address strength reduction and ret_out epilogue hoist
# speedup vs baseline: 1.0036x; 1.0003x over previous
; #define LAS __attribute__((address_space(3)))
; #define LDS_WAIT() asm volatile("s_waitcnt lgkmcnt(0)" ::: "memory")
; #define MFMA32(a, b, c) __builtin_amdgcn_mfma_f32_32x32x16_bf16((a), (b), (c), 0, 0, 0)
; __device__ __forceinline__ void phase_attn(const Frame& F, const Args& a) {
;     ...
;     for (int w = vb * NWAVES + F.wave; w < 15360; w += F.NGW) {
;         const int rest = w >> 9, seq = rest % 10, g = rest / 10, sub = w & 511, h = sub >> 7, pq = sub & 127;
;         const int d = (g == 0) ? 1 : (g == 1 ? 4 : 16), Lg = SEQ / d, nqb = Lg / 32, p = pq / nqb, qb = pq % nqb;
;         const size_t base = (size_t)seq * SEQ + (size_t)p * Lg;
;         const float slope = __builtin_amdgcn_exp2f(-8.0f * (float)(g * 4 + h + 1) / 12.0f) * (float)d;
;         const bf16* Qg = QA + (size_t)g * T * 512; const bf16* Kg = KA + (size_t)g * T * 512; const bf16* Vg = VTA + (size_t)g * 512 * T;
;         f32x16 x[5]; bool tv[5]; int sc_[5];
; #pragma unroll
;         for (int kt = 0; kt < 5; ++kt) { const int s_t = 32 * qb - 64 + 32 * kt; tv[kt] = (s_t >= 0) && (s_t < Lg); sc_[kt] = tv[kt] ? s_t : 32 * qb;
; #pragma unroll
;             for (int e = 0; e < 16; ++e) x[kt][e] = 0.f; }
;         { bf16x8 ka[8], kb[8];
;           { bf16x8 qf[8];
; #pragma unroll
;             for (int ks = 0; ks < 8; ++ks) qf[ks] = *(const bf16x8*)(Qg + ((((base + 32 * qb) >> 5) * 4 + h) * 8 + ks) * 512 + lane * 8);
; #pragma unroll
;             for (int ks = 0; ks < 8; ++ks) *(LAS bf16x8*)(Pw + li * PLD + (16 * ks + 8 * hh) * 2) = qf[ks]; }
; #pragma unroll
;           for (int ks = 0; ks < 8; ++ks) { ka[ks] = *(const bf16x8*)(Kg + ((((base + sc_[0]) >> 5) * 4 + h) * 8 + ks) * 512 + lane * 8); kb[ks] = *(const bf16x8*)(Kg + ((((base + sc_[1]) >> 5) * 4 + h) * 8 + ks) * 512 + lane * 8); }
;           asm volatile("" ::: "memory");
;           LDS_WAIT(); asm volatile("" ::: "memory");
; #pragma unroll
;           for (int ks = 0; ks < 8; ++ks) { const bf16x8 q = *(const LAS bf16x8*)(Pw + li * PLD + (16 * ks + 8 * hh) * 2); x[0] = MFMA32(ka[ks], q, x[0]); x[1] = MFMA32(kb[ks], q, x[1]); }
.LBB0_1005:
	s_ashr_i32 s4, s6, 9
	s_mul_hi_i32 s5, s4, 0x66666667
	s_lshr_b32 s7, s5, 31
	s_ashr_i32 s18, s5, 2
	s_add_i32 s18, s18, s7
	s_mul_i32 s5, s18, 10
	s_sub_i32 s8, s4, s5
	s_bfe_u32 s7, s6, 0x20007
	s_and_b32 s5, s6, 0x7f
	s_add_i32 s9, s4, 9
	s_add_i32 s4, s4, -10
	s_cmp_lt_u32 s4, 10
	s_cselect_b32 s4, 4, 16
	s_cselect_b32 s10, 2, 4
	s_cmp_lt_u32 s9, 19
	s_cselect_b32 s11, 1, s4
	s_cselect_b32 s4, 0, s10
	s_lshr_b32 s9, 0x80, s4
	s_xor_b32 s10, s4, 7
	s_add_i32 s9, s9, -1
	s_lshr_b32 s82, s5, s10
	s_and_b32 s20, s9, s5
	s_sub_i32 s5, 12, s4
	s_lshl_b32 s21, s82, s5
	s_lshl_b32 s5, s18, 2
	s_or_b32 s5, s7, s5
	s_add_i32 s5, s5, 1
	v_cvt_f32_i32_e32 v0, s5
	s_ashr_i32 s9, s8, 31
	s_mov_b32 s5, 0x41400000
	s_lshl_b64 s[14:15], s[8:9], 12
	v_mul_f32_e32 v0, 0xc1000000, v0
	v_div_scale_f32 v1, s[8:9], s5, s5, v0
	v_rcp_f32_e32 v2, v1
	s_lshr_b32 s19, 0x1000, s4
	s_movk_i32 s92, 0xffe0
	s_mov_b32 s93, 0x3fffff
	v_fma_f32 v3, -v1, v2, 1.0
	v_fmac_f32_e32 v2, v3, v2
	v_div_scale_f32 v3, vcc, v0, s5, v0
	v_mul_f32_e32 v4, v3, v2
	v_fma_f32 v5, -v1, v4, v3
	v_fmac_f32_e32 v4, v5, v2
	v_fma_f32 v1, -v1, v4, v3
	v_div_fmas_f32 v1, v1, v2, v4
	v_div_fixup_f32 v0, v1, s5, v0
	s_lshl_b32 s5, s20, 5
	s_sub_i32 s22, s5, 64
	s_cmp_gt_u32 s20, 1
	s_cselect_b64 s[8:9], -1, 0
	s_cmp_lt_i32 s22, s19
	s_cselect_b64 s[16:17], -1, 0
	s_and_b64 s[28:29], s[8:9], s[16:17]
	s_and_b64 s[8:9], s[28:29], exec
	s_cselect_b32 s23, s22, s5
	s_sub_i32 s22, s5, 32
	s_cmp_lg_u32 s20, 0
	s_cselect_b64 s[8:9], -1, 0
	s_cmp_le_u32 s5, s19
	s_cselect_b64 s[16:17], -1, 0
	s_and_b64 s[74:75], s[8:9], s[16:17]
	s_and_b64 s[8:9], s[74:75], exec
	s_cselect_b32 s68, s22, s5
	s_cmp_lt_u32 s5, s19
	s_cselect_b64 s[72:73], -1, 0
	s_add_i32 s16, s5, 32
	s_cmp_lt_u32 s16, s19
	s_cselect_b64 vcc, -1, 0
	s_and_b64 s[8:9], vcc, exec
	s_cselect_b32 s22, s16, s5
	s_add_i32 s16, s5, 64
	s_cmp_lt_u32 s16, s19
	s_cselect_b64 s[26:27], -1, 0
	s_and_b64 s[8:9], s[26:27], exec
	s_cselect_b32 s44, s16, s5
	s_add_u32 s45, s14, s21
	s_addc_u32 s86, s15, 0
	v_exp_f32_e32 v0, v0
	s_add_u32 s20, s45, s5
	s_addc_u32 s21, s86, 0
	s_lshl_b32 s87, s7, 3
	s_and_b64 s[8:9], s[20:21], s[92:93]
	v_cvt_f32_ubyte0_e32 v1, s11
	s_or_b32 s8, s8, s87
	s_waitcnt vmcnt(0)
	v_mov_b32_e32 v32, 0x2800000
	v_mul_f32_e32 v120, v0, v1
	v_mad_i64_i32 v[0:1], s[16:17], s18, v32, v[138:139]
	s_lshl_b64 s[24:25], s[8:9], 10
	v_lshl_add_u64 v[16:17], v[0:1], 0, s[24:25]
	v_add_co_u32_e64 v28, s[76:77], s33, v16
	global_load_dwordx4 v[0:3], v[16:17], off
	global_load_dwordx4 v[4:7], v[16:17], off offset:1024
	global_load_dwordx4 v[8:11], v[16:17], off offset:2048
	global_load_dwordx4 v[12:15], v[16:17], off offset:3072
	v_addc_co_u32_e64 v29, s[76:77], 0, v17, s[76:77]
	global_load_dwordx4 v[16:19], v[28:29], off
	global_load_dwordx4 v[20:23], v[28:29], off offset:1024
	global_load_dwordx4 v[24:27], v[28:29], off offset:2048
	s_nop 0
	global_load_dwordx4 v[28:31], v[28:29], off offset:3072
	s_ashr_i32 s17, s23, 31
	s_add_u32 s16, s45, s23
	s_addc_u32 s17, s86, s17
	s_mul_hi_i32 s11, s18, 0x2800000
	s_mul_i32 s10, s18, 0x2800000
	s_mul_hi_i32 s8, s18, 0xa000
	s_mul_i32 s9, s18, 0xa000
	s_and_b64 s[30:31], s[16:17], s[92:93]
	s_or_b32 s30, s30, s87
	s_waitcnt vmcnt(7)
	ds_write_b128 v238, v[0:3]
	s_waitcnt vmcnt(6)
	ds_write_b128 v238, v[4:7] offset:32
	s_waitcnt vmcnt(5)
	ds_write_b128 v238, v[8:11] offset:64
	s_waitcnt vmcnt(4)
	ds_write_b128 v238, v[12:15] offset:96
	s_waitcnt vmcnt(3)
	ds_write_b128 v238, v[16:19] offset:128
	s_waitcnt vmcnt(2)
	ds_write_b128 v238, v[20:23] offset:160
	s_waitcnt vmcnt(1)
	ds_write_b128 v238, v[24:27] offset:192
	s_waitcnt vmcnt(0)
	ds_write_b128 v238, v[28:31] offset:224
	v_mad_i64_i32 v[16:17], s[18:19], s18, v32, v[142:143]
	s_ashr_i32 s19, s68, 31
	s_add_u32 s18, s45, s68
	s_addc_u32 s19, s86, s19
	s_lshl_b64 s[30:31], s[30:31], 10
	v_lshl_add_u64 v[8:9], v[16:17], 0, s[30:31]
	global_load_dwordx4 v[0:3], v[8:9], off
	s_and_b64 s[76:77], s[18:19], s[92:93]
	s_or_b32 s76, s76, s87
	s_lshl_b64 s[30:31], s[76:77], 10
	v_lshl_add_u64 v[10:11], v[16:17], 0, s[30:31]
	global_load_dwordx4 v[4:7], v[10:11], off
	global_load_dwordx4 v[18:21], v[8:9], off offset:1024
	global_load_dwordx4 v[22:25], v[10:11], off offset:1024
	global_load_dwordx4 v[26:29], v[8:9], off offset:2048
	global_load_dwordx4 v[30:33], v[10:11], off offset:2048
	global_load_dwordx4 v[34:37], v[8:9], off offset:3072
	global_load_dwordx4 v[38:41], v[10:11], off offset:3072
	v_add_co_u32_e64 v8, s[76:77], s33, v8
	s_add_u32 s22, s45, s22
	s_nop 0
	v_addc_co_u32_e64 v9, s[76:77], 0, v9, s[76:77]
	global_load_dwordx4 v[42:45], v[8:9], off
	v_add_co_u32_e64 v10, s[76:77], s33, v10
	s_addc_u32 s23, s86, 0
	s_nop 0
	v_addc_co_u32_e64 v11, s[76:77], 0, v11, s[76:77]
	global_load_dwordx4 v[46:49], v[10:11], off
	global_load_dwordx4 v[50:53], v[8:9], off offset:1024
	global_load_dwordx4 v[54:57], v[10:11], off offset:1024
	global_load_dwordx4 v[58:61], v[8:9], off offset:2048
	global_load_dwordx4 v[80:83], v[10:11], off offset:2048
	global_load_dwordx4 v[84:87], v[8:9], off offset:3072
	global_load_dwordx4 v[88:91], v[10:11], off offset:3072
	s_waitcnt lgkmcnt(0)
	ds_read_b128 v[8:11], v238
	ds_read_b128 v[92:95], v238 offset:32
	s_and_b64 s[30:31], s[22:23], s[92:93]
	s_or_b32 s30, s30, s87
	s_waitcnt vmcnt(15) lgkmcnt(1)
	v_mfma_f32_32x32x16_bf16 v[64:79], v[0:3], v[8:11], 0
	s_waitcnt vmcnt(14)
	v_mfma_f32_32x32x16_bf16 v[0:15], v[4:7], v[8:11], 0
	s_waitcnt vmcnt(13) lgkmcnt(0)
	v_mfma_f32_32x32x16_bf16 v[64:79], v[18:21], v[92:95], v[64:79]
	ds_read_b128 v[18:21], v238 offset:64
	s_waitcnt vmcnt(12)
; #define LAS __attribute__((address_space(3)))
; #define LDS_WAIT() asm volatile("s_waitcnt lgkmcnt(0)" ::: "memory")
; #define MFMA32(a, b, c) __builtin_amdgcn_mfma_f32_32x32x16_bf16((a), (b), (c), 0, 0, 0)
; __device__ __forceinline__ void phase_attn(const Frame& F, const Args& a) {
;     ...
;           for (int ks = 0; ks < 8; ++ks) { ka[ks] = *(const bf16x8*)(Kg + ((((base + sc_[0]) >> 5) * 4 + h) * 8 + ks) * 512 + lane * 8); kb[ks] = *(const bf16x8*)(Kg + ((((base + sc_[1]) >> 5) * 4 + h) * 8 + ks) * 512 + lane * 8); }
;           asm volatile("" ::: "memory");
;           LDS_WAIT(); asm volatile("" ::: "memory");
; #pragma unroll
;           for (int ks = 0; ks < 8; ++ks) { const bf16x8 q = *(const LAS bf16x8*)(Pw + li * PLD + (16 * ks + 8 * hh) * 2); x[0] = MFMA32(ka[ks], q, x[0]); x[1] = MFMA32(kb[ks], q, x[1]); }
; #pragma unroll
;           for (int ks = 0; ks < 8; ++ks) { ka[ks] = *(const bf16x8*)(Kg + ((((base + sc_[2]) >> 5) * 4 + h) * 8 + ks) * 512 + lane * 8); kb[ks] = *(const bf16x8*)(Kg + ((((base + sc_[3]) >> 5) * 4 + h) * 8 + ks) * 512 + lane * 8); }
;           asm volatile("" ::: "memory");
; #pragma unroll
;           for (int ks = 0; ks < 8; ++ks) { const bf16x8 q = *(const LAS bf16x8*)(Pw + li * PLD + (16 * ks + 8 * hh) * 2); x[2] = MFMA32(ka[ks], q, x[2]); x[3] = MFMA32(kb[ks], q, x[3]); }
; #pragma unroll
;           for (int ks = 0; ks < 8; ++ks) ka[ks] = *(const bf16x8*)(Kg + ((((base + sc_[4]) >> 5) * 4 + h) * 8 + ks) * 512 + lane * 8);
;           asm volatile("" ::: "memory");
; #pragma unroll
;           for (int ks = 0; ks < 8; ++ks) { const bf16x8 q = *(const LAS bf16x8*)(Pw + li * PLD + (16 * ks + 8 * hh) * 2); x[4] = MFMA32(ka[ks], q, x[4]); }
;           LDS_WAIT(); asm volatile("" ::: "memory");
;         }
;     ...
;         bf16x8 vfA[5][2], vfB[5][2], vfC[5][2];
;         ATT_VLOAD(vfA, 0); asm volatile("" ::: "memory");
;         float mx = -1e30f;
; #pragma unroll
;         for (int kt = 0; kt < 5; ++kt)
; #pragma unroll
;             for (int e = 0; e < 16; ++e) { const int j = (e & 3) + 8 * (e >> 2) + 4 * hh; const int rel = 32 * kt - 64 + j - li; const int ar = rel < 0 ? -rel : rel;
;                 const bool ok = tv[kt] && ar <= 64; const float sv = ok ? (x[kt][e] - slope * (float)ar) : -1e30f; x[kt][e] = sv; mx = fmaxf(mx, sv); }
	v_mfma_f32_32x32x16_bf16 v[0:15], v[22:25], v[92:95], v[0:15]
	s_waitcnt vmcnt(11) lgkmcnt(0)
	v_mfma_f32_32x32x16_bf16 v[64:79], v[26:29], v[18:21], v[64:79]
	s_waitcnt vmcnt(10)
	v_mfma_f32_32x32x16_bf16 v[0:15], v[30:33], v[18:21], v[0:15]
	ds_read_b128 v[18:21], v238 offset:96
	v_lshl_add_u64 v[30:31], v[16:17], 0, s[24:25]
	s_lshl_b64 s[24:25], s[30:31], 10
	v_lshl_add_u64 v[32:33], v[16:17], 0, s[24:25]
	s_add_u32 s30, s45, s44
	s_addc_u32 s31, s86, 0
	s_and_b64 s[24:25], s[30:31], s[92:93]
	s_waitcnt vmcnt(9) lgkmcnt(0)
	v_mfma_f32_32x32x16_bf16 v[64:79], v[34:37], v[18:21], v[64:79]
	s_or_b32 s24, s24, s87
	s_lshl_b64 s[24:25], s[24:25], 10
	s_mul_i32 s44, s7, 0x1400
	s_waitcnt vmcnt(8)
	v_mfma_f32_32x32x16_bf16 v[0:15], v[38:41], v[18:21], v[0:15]
	ds_read_b128 v[18:21], v238 offset:128
	s_waitcnt vmcnt(7) lgkmcnt(0)
	v_mfma_f32_32x32x16_bf16 v[64:79], v[42:45], v[18:21], v[64:79]
	s_waitcnt vmcnt(6)
	v_mfma_f32_32x32x16_bf16 v[0:15], v[46:49], v[18:21], v[0:15]
	ds_read_b128 v[18:21], v238 offset:160
	s_waitcnt vmcnt(5) lgkmcnt(0)
	v_mfma_f32_32x32x16_bf16 v[64:79], v[50:53], v[18:21], v[64:79]
	s_waitcnt vmcnt(4)
	v_mfma_f32_32x32x16_bf16 v[0:15], v[54:57], v[18:21], v[0:15]
	ds_read_b128 v[18:21], v238 offset:192
	s_waitcnt vmcnt(3) lgkmcnt(0)
	v_mfma_f32_32x32x16_bf16 v[64:79], v[58:61], v[18:21], v[64:79]
	s_waitcnt vmcnt(2)
	v_mfma_f32_32x32x16_bf16 v[0:15], v[80:83], v[18:21], v[0:15]
	ds_read_b128 v[18:21], v238 offset:224
	s_waitcnt vmcnt(1) lgkmcnt(0)
	v_mfma_f32_32x32x16_bf16 v[64:79], v[84:87], v[18:21], v[64:79]
	s_waitcnt vmcnt(0)
	v_mfma_f32_32x32x16_bf16 v[0:15], v[88:91], v[18:21], v[0:15]
	global_load_dwordx4 v[18:21], v[30:31], off
	global_load_dwordx4 v[22:25], v[32:33], off
	global_load_dwordx4 v[26:29], v[30:31], off offset:1024
	global_load_dwordx4 v[80:83], v[32:33], off offset:1024
	global_load_dwordx4 v[84:87], v[30:31], off offset:2048
	global_load_dwordx4 v[88:91], v[32:33], off offset:2048
	global_load_dwordx4 v[92:95], v[30:31], off offset:3072
	global_load_dwordx4 v[96:99], v[32:33], off offset:3072
	v_add_co_u32_e64 v30, s[76:77], s33, v30
	s_nop 0
	v_fma_f32 v64, -v120, v148, v64
	v_addc_co_u32_e64 v31, s[76:77], 0, v31, s[76:77]
	global_load_dwordx4 v[100:103], v[30:31], off
	v_add_co_u32_e64 v32, s[76:77], s33, v32
	v_fma_f32 v0, -v120, v164, v0
	s_nop 0
	v_addc_co_u32_e64 v33, s[76:77], 0, v33, s[76:77]
	global_load_dwordx4 v[104:107], v[32:33], off
	global_load_dwordx4 v[108:111], v[30:31], off offset:1024
	global_load_dwordx4 v[112:115], v[32:33], off offset:1024
	global_load_dwordx4 v[116:119], v[30:31], off offset:2048
	global_load_dwordx4 v[122:125], v[32:33], off offset:2048
	global_load_dwordx4 v[126:129], v[30:31], off offset:3072
	global_load_dwordx4 v[130:133], v[32:33], off offset:3072
	ds_read_b128 v[30:33], v238
	ds_read_b128 v[240:243], v238 offset:32
	s_waitcnt vmcnt(15) lgkmcnt(1)
	v_mfma_f32_32x32x16_bf16 v[48:63], v[18:21], v[30:33], 0
	ds_read_b128 v[18:21], v238 offset:64
	v_cndmask_b32_e64 v251, v209, v0, s[74:75]
	v_fma_f32 v0, -v120, v165, v1
	v_fma_f32 v1, -v120, v166, v2
	v_cndmask_b32_e64 v249, v209, v1, s[74:75]
	v_fma_f32 v1, -v120, v167, v3
	v_cndmask_b32_e64 v248, v209, v1, s[74:75]
	s_waitcnt vmcnt(14)
	v_mfma_f32_32x32x16_bf16 v[32:47], v[22:25], v[30:33], 0
	v_fma_f32 v1, -v120, v168, v4
	v_cndmask_b32_e64 v247, v209, v1, s[74:75]
	v_fma_f32 v1, -v120, v169, v5
	v_cndmask_b32_e64 v245, v209, v1, s[74:75]
	v_fma_f32 v1, -v120, v170, v6
	v_cndmask_b32_e64 v244, v209, v1, s[74:75]
	v_fma_f32 v1, -v120, v171, v7
	s_waitcnt vmcnt(13) lgkmcnt(1)
	v_mfma_f32_32x32x16_bf16 v[48:63], v[26:29], v[240:243], v[48:63]
	v_cndmask_b32_e64 v250, v209, v0, s[74:75]
	s_waitcnt vmcnt(12)
	v_mfma_f32_32x32x16_bf16 v[32:47], v[80:83], v[240:243], v[32:47]
	v_cndmask_b32_e64 v243, v209, v1, s[74:75]
	v_fma_f32 v1, -v120, v172, v8
	v_cndmask_b32_e64 v241, v209, v1, s[74:75]
	v_fma_f32 v1, -v120, v173, v9
	v_cndmask_b32_e64 v239, v209, v1, s[74:75]
	v_fma_f32 v1, -v120, v174, v10
	v_cndmask_b32_e64 v145, v209, v1, s[74:75]
	s_waitcnt vmcnt(11) lgkmcnt(0)
	v_mfma_f32_32x32x16_bf16 v[48:63], v[84:87], v[18:21], v[48:63]
	v_fma_f32 v1, -v120, v175, v11
	s_waitcnt vmcnt(10)
	v_mfma_f32_32x32x16_bf16 v[32:47], v[88:91], v[18:21], v[32:47]
	ds_read_b128 v[18:21], v238 offset:96
	s_waitcnt vmcnt(9) lgkmcnt(0)
	v_mfma_f32_32x32x16_bf16 v[48:63], v[92:95], v[18:21], v[48:63]
	s_waitcnt vmcnt(8)
	v_mfma_f32_32x32x16_bf16 v[32:47], v[96:99], v[18:21], v[32:47]
	ds_read_b128 v[18:21], v238 offset:128
	s_waitcnt vmcnt(7) lgkmcnt(0)
	v_mfma_f32_32x32x16_bf16 v[48:63], v[100:103], v[18:21], v[48:63]
	s_waitcnt vmcnt(6)
	v_mfma_f32_32x32x16_bf16 v[32:47], v[104:107], v[18:21], v[32:47]
	ds_read_b128 v[18:21], v238 offset:160
	s_waitcnt vmcnt(5) lgkmcnt(0)
	v_mfma_f32_32x32x16_bf16 v[48:63], v[108:111], v[18:21], v[48:63]
	s_waitcnt vmcnt(4)
	v_mfma_f32_32x32x16_bf16 v[32:47], v[112:115], v[18:21], v[32:47]
	ds_read_b128 v[18:21], v238 offset:192
	s_waitcnt vmcnt(3) lgkmcnt(0)
	v_mfma_f32_32x32x16_bf16 v[48:63], v[116:119], v[18:21], v[48:63]
	s_waitcnt vmcnt(2)
	v_mfma_f32_32x32x16_bf16 v[32:47], v[122:125], v[18:21], v[32:47]
	ds_read_b128 v[18:21], v238 offset:224
	s_waitcnt vmcnt(1) lgkmcnt(0)
	v_mfma_f32_32x32x16_bf16 v[48:63], v[126:129], v[18:21], v[48:63]
	s_waitcnt vmcnt(0)
; #define LAS __attribute__((address_space(3)))
; #define LDS_WAIT() asm volatile("s_waitcnt lgkmcnt(0)" ::: "memory")
; #define MFMA32(a, b, c) __builtin_amdgcn_mfma_f32_32x32x16_bf16((a), (b), (c), 0, 0, 0)
; #define ATT_VLOAD(VF, dt_) do { _Pragma("unroll") for (int kt = 0; kt < 5; ++kt) _Pragma("unroll") for (int k2 = 0; k2 < 2; ++k2) \
;             VF[kt][k2] = ldfrag(Vg + ((((size_t)(h * 4 + (dt_)) * (T / 32) + ((base + sc_[kt]) >> 5)) * 2 + k2) * 512), (unsigned)lane * 16u); } while (0)
; __device__ __forceinline__ void phase_attn(const Frame& F, const Args& a) {
;     ...
;           for (int ks = 0; ks < 8; ++ks) ka[ks] = *(const bf16x8*)(Kg + ((((base + sc_[4]) >> 5) * 4 + h) * 8 + ks) * 512 + lane * 8);
;           asm volatile("" ::: "memory");
; #pragma unroll
;           for (int ks = 0; ks < 8; ++ks) { const bf16x8 q = *(const LAS bf16x8*)(Pw + li * PLD + (16 * ks + 8 * hh) * 2); x[4] = MFMA32(ka[ks], q, x[4]); }
;           LDS_WAIT(); asm volatile("" ::: "memory");
;         }
;     ...
;         bf16x8 vfA[5][2], vfB[5][2], vfC[5][2];
;         ATT_VLOAD(vfA, 0); asm volatile("" ::: "memory");
;         float mx = -1e30f;
; #pragma unroll
;         for (int kt = 0; kt < 5; ++kt)
; #pragma unroll
;             for (int e = 0; e < 16; ++e) { const int j = (e & 3) + 8 * (e >> 2) + 4 * hh; const int rel = 32 * kt - 64 + j - li; const int ar = rel < 0 ? -rel : rel;
;                 const bool ok = tv[kt] && ar <= 64; const float sv = ok ? (x[kt][e] - slope * (float)ar) : -1e30f; x[kt][e] = sv; mx = fmaxf(mx, sv); }
	v_mfma_f32_32x32x16_bf16 v[32:47], v[130:133], v[18:21], v[32:47]
	v_lshl_add_u64 v[20:21], v[16:17], 0, s[24:25]
	global_load_dwordx4 v[16:19], v[20:21], off
	global_load_dwordx4 v[80:83], v[20:21], off offset:1024
	global_load_dwordx4 v[84:87], v[20:21], off offset:2048
	global_load_dwordx4 v[88:91], v[20:21], off offset:3072
	v_add_co_u32_e64 v20, s[76:77], s33, v20
	v_readlane_b32 s24, v255, 7
	s_nop 0
	v_addc_co_u32_e64 v21, s[76:77], 0, v21, s[76:77]
	global_load_dwordx4 v[92:95], v[20:21], off
	global_load_dwordx4 v[96:99], v[20:21], off offset:1024
	global_load_dwordx4 v[100:103], v[20:21], off offset:2048
	global_load_dwordx4 v[104:107], v[20:21], off offset:3072
	ds_read_b128 v[20:23], v238
	ds_read_b128 v[108:111], v238 offset:32
	s_waitcnt vmcnt(7) lgkmcnt(1)
	v_mfma_f32_32x32x16_bf16 v[16:31], v[16:19], v[20:23], 0
	s_add_u32 s10, s24, s10
	v_readlane_b32 s24, v255, 9
	s_addc_u32 s11, s24, s11
	s_lshr_b64 s[16:17], s[16:17], 5
	s_add_u32 s24, s16, s44
	s_addc_u32 s25, s17, 0
	s_lshl_b64 s[24:25], s[24:25], 11
	s_waitcnt vmcnt(6) lgkmcnt(0)
	v_mfma_f32_32x32x16_bf16 v[16:31], v[80:83], v[108:111], v[16:31]
	ds_read_b128 v[80:83], v238 offset:64
	s_add_u32 s24, s10, s24
	s_addc_u32 s25, s11, s25
	s_mov_b64 s[76:77], s[24:25]
	s_add_u32 s24, s24, 0x400
	s_addc_u32 s25, s25, 0
	s_lshr_b64 s[18:19], s[18:19], 5
	s_waitcnt vmcnt(5) lgkmcnt(0)
	v_mfma_f32_32x32x16_bf16 v[16:31], v[84:87], v[80:83], v[16:31]
	ds_read_b128 v[80:83], v238 offset:96
	v_cndmask_b32_e64 v132, v209, v1, s[74:75]
	v_fma_f32 v1, -v120, v176, v12
	v_cndmask_b32_e64 v127, v209, v1, s[74:75]
	v_fma_f32 v1, -v120, v177, v13
	s_waitcnt vmcnt(4) lgkmcnt(0)
	v_mfma_f32_32x32x16_bf16 v[16:31], v[88:91], v[80:83], v[16:31]
	ds_read_b128 v[80:83], v238 offset:128
	s_waitcnt vmcnt(3) lgkmcnt(0)
	v_mfma_f32_32x32x16_bf16 v[16:31], v[92:95], v[80:83], v[16:31]
	ds_read_b128 v[80:83], v238 offset:160
	s_waitcnt vmcnt(2) lgkmcnt(0)
	v_mfma_f32_32x32x16_bf16 v[16:31], v[96:99], v[80:83], v[16:31]
	ds_read_b128 v[80:83], v238 offset:192
	s_waitcnt vmcnt(1) lgkmcnt(0)
	v_mfma_f32_32x32x16_bf16 v[16:31], v[100:103], v[80:83], v[16:31]
	ds_read_b128 v[80:83], v238 offset:224
	s_waitcnt lgkmcnt(0)
	s_waitcnt vmcnt(0) lgkmcnt(0)
	v_mfma_f32_32x32x16_bf16 v[16:31], v[104:107], v[80:83], v[16:31]
	v_lshl_add_u64 v[80:81], s[76:77], 0, v[136:137]
	global_load_dwordx4 v[80:83], v[80:81], off
	s_nop 0
	v_lshl_add_u64 v[84:85], s[24:25], 0, v[136:137]
	s_add_u32 s24, s18, s44
	s_addc_u32 s25, s19, 0
	s_lshl_b64 s[24:25], s[24:25], 11
	s_add_u32 s24, s10, s24
	s_addc_u32 s25, s11, s25
	s_mov_b64 s[76:77], s[24:25]
	s_add_u32 s24, s24, 0x400
	global_load_dwordx4 v[84:87], v[84:85], off
	s_addc_u32 s25, s25, 0
	v_lshl_add_u64 v[88:89], s[76:77], 0, v[136:137]
	global_load_dwordx4 v[88:91], v[88:89], off
	s_nop 0
	v_lshl_add_u64 v[92:93], s[24:25], 0, v[136:137]
	s_lshr_b64 s[24:25], s[20:21], 5
	s_add_u32 s20, s24, s44
	s_addc_u32 s21, s25, 0
	s_lshl_b64 s[20:21], s[20:21], 11
	s_add_u32 s20, s10, s20
	s_addc_u32 s21, s11, s21
	s_mov_b64 s[76:77], s[20:21]
	s_add_u32 s20, s20, 0x400
	global_load_dwordx4 v[92:95], v[92:93], off
	s_addc_u32 s21, s21, 0
	v_lshl_add_u64 v[96:97], s[76:77], 0, v[136:137]
	global_load_dwordx4 v[100:103], v[96:97], off
	s_lshr_b64 s[22:23], s[22:23], 5
	v_lshl_add_u64 v[96:97], s[20:21], 0, v[136:137]
	s_add_u32 s20, s22, s44
	s_addc_u32 s21, s23, 0
	s_lshl_b64 s[20:21], s[20:21], 11
	s_add_u32 s20, s10, s20
	s_addc_u32 s21, s11, s21
	s_mov_b64 s[76:77], s[20:21]
	s_add_u32 s20, s20, 0x400
	global_load_dwordx4 v[96:99], v[96:97], off
	s_addc_u32 s21, s21, 0
	v_lshl_add_u64 v[104:105], s[76:77], 0, v[136:137]
	global_load_dwordx4 v[112:115], v[104:105], off
	s_nop 0
	v_lshl_add_u64 v[104:105], s[20:21], 0, v[136:137]
	s_lshr_b64 s[20:21], s[30:31], 5
	s_add_u32 s30, s20, s44
	s_addc_u32 s31, s21, 0
	s_lshl_b64 s[30:31], s[30:31], 11
	s_add_u32 s30, s10, s30
	s_addc_u32 s31, s11, s31
	s_mov_b64 s[76:77], s[30:31]
	s_add_u32 s30, s30, 0x400
	global_load_dwordx4 v[104:107], v[104:105], off
	s_addc_u32 s31, s31, 0
	v_lshl_add_u64 v[108:109], s[76:77], 0, v[136:137]
	global_load_dwordx4 v[116:119], v[108:109], off
	s_nop 0
	v_lshl_add_u64 v[108:109], s[30:31], 0, v[136:137]
	v_readlane_b32 s30, v255, 13
	v_readlane_b32 s31, v255, 14
	s_and_b64 s[76:77], s[28:29], s[30:31]
	v_readlane_b32 s30, v255, 31
	v_readlane_b32 s31, v255, 32
	v_cndmask_b32_e64 v144, v209, v64, s[76:77]
	s_and_b64 s[76:77], s[28:29], s[30:31]
	v_fma_f32 v64, -v120, v149, v65
	v_cndmask_b32_e64 v133, v209, v64, s[76:77]
	s_mov_b32 s30, 0xf149f2ca
	v_max3_f32 v64, v144, s30, v133
	v_readlane_b32 s30, v255, 33
	v_readlane_b32 s31, v255, 34
	s_and_b64 s[76:77], s[28:29], s[30:31]
	v_readlane_b32 s30, v255, 35
	v_fma_f32 v65, -v120, v150, v66
	v_readlane_b32 s31, v255, 36
	v_cndmask_b32_e64 v134, v209, v65, s[76:77]
	s_and_b64 s[76:77], s[28:29], s[30:31]
	v_readlane_b32 s30, v255, 37
	v_fma_f32 v65, -v120, v151, v67
	v_readlane_b32 s31, v255, 38
	v_cndmask_b32_e64 v131, v209, v65, s[76:77]
	s_and_b64 s[76:77], s[28:29], s[30:31]
	v_readlane_b32 s30, v255, 39
	v_fma_f32 v65, -v120, v152, v68
	v_readlane_b32 s31, v255, 40
	v_cndmask_b32_e64 v130, v209, v65, s[76:77]
	s_and_b64 s[76:77], s[28:29], s[30:31]
	v_readlane_b32 s30, v255, 41
	v_fma_f32 v65, -v120, v153, v69
	v_readlane_b32 s31, v255, 42
	v_cndmask_b32_e64 v128, v209, v65, s[76:77]
	s_and_b64 s[76:77], s[28:29], s[30:31]
	v_readlane_b32 s30, v255, 43
	v_fma_f32 v65, -v120, v154, v70
	v_readlane_b32 s31, v255, 44
	v_cndmask_b32_e64 v126, v209, v65, s[76:77]
	s_and_b64 s[76:77], s[28:29], s[30:31]
	v_readlane_b32 s30, v255, 45
; __device__ __forceinline__ float shfl_xor_(float v, int m) { return __builtin_bit_cast(float, __builtin_amdgcn_ds_bpermute((lane_id() ^ m) << 2, __builtin_bit_cast(int, v))); }
; __device__ __forceinline__ void phase_attn(const Frame& F, const Args& a) {
;     ...
;         for (int kt = 0; kt < 5; ++kt)
; #pragma unroll
;             for (int e = 0; e < 16; ++e) { const int j = (e & 3) + 8 * (e >> 2) + 4 * hh; const int rel = 32 * kt - 64 + j - li; const int ar = rel < 0 ? -rel : rel;
;                 const bool ok = tv[kt] && ar <= 64; const float sv = ok ? (x[kt][e] - slope * (float)ar) : -1e30f; x[kt][e] = sv; mx = fmaxf(mx, sv); }
;         mx = fmaxf(mx, shfl_xor_(mx, 32));
	v_fma_f32 v65, -v120, v155, v71
	v_readlane_b32 s31, v255, 46
	v_cndmask_b32_e64 v125, v209, v65, s[76:77]
	s_and_b64 s[76:77], s[28:29], s[30:31]
	v_readlane_b32 s30, v255, 47
	v_fma_f32 v65, -v120, v156, v72
	v_readlane_b32 s31, v255, 48
	v_cndmask_b32_e64 v124, v209, v65, s[76:77]
	s_and_b64 s[76:77], s[28:29], s[30:31]
	v_readlane_b32 s30, v255, 49
	v_fma_f32 v65, -v120, v157, v73
	v_readlane_b32 s31, v255, 50
	v_cndmask_b32_e64 v123, v209, v65, s[76:77]
	s_and_b64 s[76:77], s[28:29], s[30:31]
	v_readlane_b32 s30, v255, 51
	v_fma_f32 v65, -v120, v158, v74
	v_readlane_b32 s31, v255, 52
	v_cndmask_b32_e64 v122, v209, v65, s[76:77]
	s_and_b64 s[76:77], s[28:29], s[30:31]
	v_fma_f32 v65, -v120, v159, v75
	v_cndmask_b32_e64 v74, v209, v65, s[76:77]
	v_fma_f32 v65, -v120, v160, v76
	v_cndmask_b32_e64 v76, v209, v1, s[74:75]
	v_fma_f32 v1, -v120, v178, v14
	v_cndmask_b32_e64 v68, v209, v1, s[74:75]
	v_fma_f32 v1, -v120, v179, v15
	v_readlane_b32 s30, v254, 60
	v_cndmask_b32_e64 v242, v209, v1, s[74:75]
	v_fma_f32 v1, -v120, v180, v48
	v_readlane_b32 s31, v254, 61
	v_cndmask_b32_e64 v240, v209, v1, s[72:73]
	v_fma_f32 v1, -v120, v181, v49
	s_and_b64 s[76:77], s[28:29], s[30:31]
	v_readlane_b32 s30, v255, 15
	v_cndmask_b32_e64 v184, v209, v1, s[72:73]
	v_fma_f32 v1, -v120, v182, v50
	v_readlane_b32 s31, v255, 16
	v_cndmask_b32_e64 v135, v209, v1, s[72:73]
	v_fma_f32 v1, -v120, v183, v51
	v_cndmask_b32_e64 v72, v209, v65, s[76:77]
	s_and_b64 s[76:77], s[28:29], s[30:31]
	v_fma_f32 v65, -v120, v161, v77
	v_cndmask_b32_e64 v129, v209, v1, s[72:73]
	v_fma_f32 v1, -v120, v186, v52
	v_cndmask_b32_e64 v69, v209, v65, s[76:77]
	v_fma_f32 v65, -v120, v162, v78
	v_cndmask_b32_e64 v78, v209, v1, s[72:73]
	v_fma_f32 v1, -v120, v188, v53
	v_cndmask_b32_e64 v121, v209, v1, s[72:73]
	v_fma_f32 v1, -v120, v189, v54
	v_fma_f32 v66, -v120, v163, v79
	v_cndmask_b32_e64 v79, v209, v1, s[72:73]
	v_fma_f32 v1, -v120, v190, v55
	v_max3_f32 v64, v64, v134, v131
	v_readlane_b32 s30, v255, 17
	v_cndmask_b32_e64 v77, v209, v1, s[72:73]
	v_fma_f32 v1, -v120, v191, v56
	v_max3_f32 v64, v64, v130, v128
	v_readlane_b32 s31, v255, 18
	v_cndmask_b32_e64 v75, v209, v1, s[72:73]
	v_fma_f32 v1, -v120, v192, v57
	v_max3_f32 v64, v64, v126, v125
	s_and_b64 s[76:77], s[28:29], s[30:31]
	v_readlane_b32 s30, v255, 19
	v_cndmask_b32_e64 v73, v209, v1, s[72:73]
	v_fma_f32 v1, -v120, v193, v58
	v_max3_f32 v64, v64, v124, v123
	v_readlane_b32 s31, v255, 20
	v_cndmask_b32_e64 v71, v209, v1, s[72:73]
	v_fma_f32 v1, -v120, v194, v59
	v_max3_f32 v64, v64, v122, v74
	v_cndmask_b32_e64 v65, v209, v65, s[76:77]
	s_and_b64 s[76:77], s[28:29], s[30:31]
	v_cndmask_b32_e64 v70, v209, v1, s[72:73]
	v_fma_f32 v1, -v120, v195, v60
	v_max3_f32 v64, v64, v72, v69
	v_cndmask_b32_e64 v246, v209, v66, s[76:77]
	v_cndmask_b32_e64 v67, v209, v1, s[72:73]
	v_fma_f32 v1, -v120, v196, v61
	v_max3_f32 v64, v64, v65, v246
	v_cndmask_b32_e64 v66, v209, v1, s[72:73]
	v_fma_f32 v1, -v120, v197, v62
	v_max3_f32 v0, v64, v251, v250
	v_cndmask_b32_e64 v64, v209, v1, s[72:73]
	v_fma_f32 v1, -v120, v198, v63
	v_cndmask_b32_e64 v62, v209, v1, s[72:73]
	v_fma_f32 v1, -v120, v199, v32
	v_cndmask_b32_e32 v61, v209, v1, vcc
	v_fma_f32 v1, -v120, v200, v33
	v_cndmask_b32_e32 v58, v209, v1, vcc
	v_fma_f32 v1, -v120, v201, v34
	v_cndmask_b32_e32 v57, v209, v1, vcc
	v_fma_f32 v1, -v120, v202, v35
	v_cndmask_b32_e32 v55, v209, v1, vcc
	v_fma_f32 v1, -v120, v203, v36
	v_cndmask_b32_e32 v54, v209, v1, vcc
	v_fma_f32 v1, -v120, v211, v37
	v_max3_f32 v0, v0, v249, v248
	v_cndmask_b32_e32 v53, v209, v1, vcc
	v_fma_f32 v1, -v120, v212, v38
	v_max3_f32 v0, v0, v247, v245
	v_cndmask_b32_e32 v52, v209, v1, vcc
	v_fma_f32 v1, -v120, v213, v39
	v_max3_f32 v0, v0, v244, v243
	v_cndmask_b32_e32 v51, v209, v1, vcc
	v_fma_f32 v1, -v120, v214, v40
	v_max3_f32 v0, v0, v241, v239
	v_cndmask_b32_e32 v50, v209, v1, vcc
	v_fma_f32 v1, -v120, v215, v41
	v_max3_f32 v0, v0, v145, v132
	v_cndmask_b32_e32 v49, v209, v1, vcc
	v_fma_f32 v1, -v120, v216, v42
	v_max3_f32 v0, v0, v127, v76
	v_cndmask_b32_e32 v48, v209, v1, vcc
	v_fma_f32 v1, -v120, v217, v43
	v_max3_f32 v0, v0, v68, v242
	v_cndmask_b32_e32 v43, v209, v1, vcc
	v_fma_f32 v1, -v120, v218, v44
	v_max3_f32 v0, v0, v240, v184
	v_cndmask_b32_e32 v42, v209, v1, vcc
	v_fma_f32 v1, -v120, v219, v45
	v_max3_f32 v0, v0, v135, v129
	v_cndmask_b32_e32 v41, v209, v1, vcc
	v_fma_f32 v1, -v120, v220, v46
	v_readlane_b32 s28, v255, 21
	v_max3_f32 v0, v0, v78, v121
	v_cndmask_b32_e32 v40, v209, v1, vcc
	v_fma_f32 v1, -v120, v221, v47
	v_readlane_b32 s29, v255, 22
	v_max3_f32 v0, v0, v79, v77
	v_cndmask_b32_e32 v38, v209, v1, vcc
	s_and_b64 vcc, s[26:27], s[28:29]
	v_readlane_b32 s28, v255, 23
	v_max3_f32 v0, v0, v75, v73
	v_fma_f32 v1, -v120, v222, v16
	v_readlane_b32 s29, v255, 24
	v_max3_f32 v0, v0, v71, v70
	v_cndmask_b32_e32 v39, v209, v1, vcc
	s_and_b64 vcc, s[26:27], s[28:29]
	v_readlane_b32 s28, v255, 25
	v_max3_f32 v0, v0, v67, v66
	v_fma_f32 v1, -v120, v223, v17
	v_readlane_b32 s29, v255, 26
	v_max3_f32 v0, v0, v64, v62
	v_cndmask_b32_e32 v37, v209, v1, vcc
	s_and_b64 vcc, s[26:27], s[28:29]
	v_fma_f32 v1, -v120, v224, v18
	v_max3_f32 v0, v0, v61, v58
	v_cndmask_b32_e32 v36, v209, v1, vcc
	s_and_b64 vcc, s[26:27], s[46:47]
	v_fma_f32 v1, -v120, v225, v19
	v_max3_f32 v0, v0, v57, v55
	v_cndmask_b32_e32 v35, v209, v1, vcc
	s_and_b64 vcc, s[26:27], s[48:49]
	v_fma_f32 v1, -v120, v226, v20
	v_max3_f32 v0, v0, v54, v53
	v_cndmask_b32_e32 v34, v209, v1, vcc
	s_and_b64 vcc, s[26:27], s[50:51]
	v_fma_f32 v1, -v120, v227, v21
	v_max3_f32 v0, v0, v52, v51
	v_cndmask_b32_e32 v33, v209, v1, vcc
; __device__ __forceinline__ float fexp(float x) { return __builtin_amdgcn_exp2f(x * 1.44269504089f); }
; __device__ __forceinline__ float shfl_xor_(float v, int m) { return __builtin_bit_cast(float, __builtin_amdgcn_ds_bpermute((lane_id() ^ m) << 2, __builtin_bit_cast(int, v))); }
; __device__ __forceinline__ void phase_attn(const Frame& F, const Args& a) {
;     ...
;         mx = fmaxf(mx, shfl_xor_(mx, 32));
;         float sum = 0.f;
; #pragma unroll
;         for (int kt = 0; kt < 5; ++kt)
; #pragma unroll
;             for (int e = 0; e < 16; ++e) { const float pv = (x[kt][e] > -1e29f) ? fexp(x[kt][e] - mx) : 0.f; x[kt][e] = pv; sum += pv; }
;         sum += shfl_xor_(sum, 32);
;         const float inv = 1.0f / sum;
;         if (hh == 0) { const size_t tok = (size_t)seq * SEQ + (size_t)(32 * qb + li) * d + p; LSE[((size_t)g * T + tok) * 4 + h] = mx + __builtin_amdgcn_logf(sum) * 0.69314718056f; }
	s_and_b64 vcc, s[26:27], s[52:53]
	v_fma_f32 v1, -v120, v228, v22
	v_max3_f32 v0, v0, v50, v49
	v_cndmask_b32_e32 v32, v209, v1, vcc
	s_and_b64 vcc, s[26:27], s[54:55]
	v_fma_f32 v1, -v120, v229, v23
	v_max3_f32 v0, v0, v48, v43
	v_cndmask_b32_e32 v22, v209, v1, vcc
	s_and_b64 vcc, s[26:27], s[56:57]
	v_fma_f32 v1, -v120, v230, v24
	v_max3_f32 v0, v0, v42, v41
	v_cndmask_b32_e32 v20, v209, v1, vcc
	s_and_b64 vcc, s[26:27], s[58:59]
	v_fma_f32 v1, -v120, v231, v25
	v_max3_f32 v0, v0, v40, v38
	v_cndmask_b32_e32 v19, v209, v1, vcc
	s_and_b64 vcc, s[26:27], s[60:61]
	v_fma_f32 v1, -v120, v232, v26
	v_max3_f32 v0, v0, v39, v37
	v_cndmask_b32_e32 v18, v209, v1, vcc
	s_and_b64 vcc, s[26:27], s[62:63]
	v_fma_f32 v1, -v120, v233, v27
	v_max3_f32 v0, v0, v36, v35
	v_cndmask_b32_e32 v16, v209, v1, vcc
	s_and_b64 vcc, s[26:27], s[64:65]
	v_fma_f32 v1, -v120, v234, v28
	v_max3_f32 v0, v0, v34, v33
	v_cndmask_b32_e32 v15, v209, v1, vcc
	s_and_b64 vcc, s[26:27], s[66:67]
	v_fma_f32 v1, -v120, v235, v29
	v_max3_f32 v0, v0, v32, v22
	v_cndmask_b32_e32 v13, v209, v1, vcc
	s_and_b64 vcc, s[26:27], s[34:35]
	v_fma_f32 v1, -v120, v236, v30
	v_max3_f32 v0, v0, v20, v19
	v_cndmask_b32_e32 v12, v209, v1, vcc
	s_and_b64 vcc, s[26:27], s[70:71]
	v_fma_f32 v1, -v120, v237, v31
	global_load_dwordx4 v[108:111], v[108:109], off
	v_max3_f32 v0, v0, v18, v16
	v_cndmask_b32_e32 v21, v209, v1, vcc
	v_mbcnt_lo_u32_b32 v1, -1, 0
	v_mbcnt_hi_u32_b32 v1, -1, v1
	v_max3_f32 v0, v0, v15, v13
	v_lshlrev_b32_e32 v1, 2, v1
	v_max3_f32 v0, v0, v12, v21
	v_xor_b32_e32 v1, 0x80, v1
	ds_bpermute_b32 v1, v1, v0
	s_waitcnt lgkmcnt(0)
	v_max_f32_e32 v1, v1, v1
	v_max_f32_e32 v2, v0, v1
	v_sub_f32_e32 v0, v144, v2
	v_mul_f32_e32 v0, 0x3fb8aa3b, v0
	v_sub_f32_e32 v1, v133, v2
	v_exp_f32_e32 v0, v0
	v_mul_f32_e32 v1, 0x3fb8aa3b, v1
	v_exp_f32_e32 v1, v1
	v_add_f32_e32 v3, 0, v0
	s_nop 0
	v_add_f32_e32 v4, v1, v3
	v_sub_f32_e32 v3, v134, v2
	v_mul_f32_e32 v3, 0x3fb8aa3b, v3
	v_exp_f32_e32 v3, v3
	s_nop 1
	v_add_f32_e32 v5, v3, v4
	v_sub_f32_e32 v4, v131, v2
	v_mul_f32_e32 v4, 0x3fb8aa3b, v4
	v_exp_f32_e32 v4, v4
	s_nop 1
	v_add_f32_e32 v6, v4, v5
	v_sub_f32_e32 v5, v130, v2
	v_mul_f32_e32 v5, 0x3fb8aa3b, v5
	v_exp_f32_e32 v5, v5
	s_nop 1
	v_add_f32_e32 v7, v5, v6
	v_sub_f32_e32 v6, v128, v2
	v_mul_f32_e32 v6, 0x3fb8aa3b, v6
	v_exp_f32_e32 v6, v6
	s_nop 1
	v_add_f32_e32 v8, v6, v7
	v_sub_f32_e32 v7, v126, v2
	v_mul_f32_e32 v7, 0x3fb8aa3b, v7
	v_exp_f32_e32 v7, v7
	s_nop 1
	v_add_f32_e32 v9, v7, v8
	v_sub_f32_e32 v8, v125, v2
	v_mul_f32_e32 v8, 0x3fb8aa3b, v8
	v_exp_f32_e32 v8, v8
	s_nop 1
	v_add_f32_e32 v10, v8, v9
	v_sub_f32_e32 v9, v124, v2
	v_mul_f32_e32 v9, 0x3fb8aa3b, v9
	v_exp_f32_e32 v9, v9
	s_nop 1
	v_add_f32_e32 v11, v9, v10
	v_sub_f32_e32 v10, v123, v2
	v_mul_f32_e32 v10, 0x3fb8aa3b, v10
	v_exp_f32_e32 v10, v10
	s_nop 1
	v_add_f32_e32 v14, v10, v11
	v_sub_f32_e32 v11, v122, v2
	v_mul_f32_e32 v11, 0x3fb8aa3b, v11
	v_exp_f32_e32 v11, v11
	s_nop 1
	v_add_f32_e32 v17, v11, v14
	v_sub_f32_e32 v14, v74, v2
	v_mul_f32_e32 v14, 0x3fb8aa3b, v14
	v_exp_f32_e32 v14, v14
	s_nop 1
	v_add_f32_e32 v23, v14, v17
	v_sub_f32_e32 v17, v72, v2
	v_mul_f32_e32 v17, 0x3fb8aa3b, v17
	v_exp_f32_e32 v17, v17
	s_nop 1
	v_add_f32_e32 v24, v17, v23
	v_sub_f32_e32 v23, v69, v2
	v_mul_f32_e32 v23, 0x3fb8aa3b, v23
	v_exp_f32_e32 v23, v23
	s_nop 1
	v_add_f32_e32 v25, v23, v24
	v_sub_f32_e32 v24, v65, v2
	v_mul_f32_e32 v24, 0x3fb8aa3b, v24
	v_exp_f32_e32 v24, v24
	s_nop 1
	v_add_f32_e32 v26, v24, v25
	v_sub_f32_e32 v25, v246, v2
	v_mul_f32_e32 v25, 0x3fb8aa3b, v25
	v_exp_f32_e32 v25, v25
	s_nop 1
	v_add_f32_e32 v27, v25, v26
	v_sub_f32_e32 v26, v251, v2
	v_mul_f32_e32 v26, 0x3fb8aa3b, v26
	v_exp_f32_e32 v26, v26
	s_nop 1
	v_add_f32_e32 v28, v26, v27
	v_sub_f32_e32 v27, v250, v2
	v_mul_f32_e32 v27, 0x3fb8aa3b, v27
	v_exp_f32_e32 v27, v27
	s_nop 1
	v_add_f32_e32 v29, v27, v28
	v_sub_f32_e32 v28, v249, v2
	v_mul_f32_e32 v28, 0x3fb8aa3b, v28
	v_exp_f32_e32 v28, v28
	s_nop 1
	v_add_f32_e32 v30, v28, v29
	v_sub_f32_e32 v29, v248, v2
	v_mul_f32_e32 v29, 0x3fb8aa3b, v29
	v_exp_f32_e32 v29, v29
	s_nop 1
	v_add_f32_e32 v31, v29, v30
	v_sub_f32_e32 v30, v247, v2
	v_mul_f32_e32 v30, 0x3fb8aa3b, v30
	v_exp_f32_e32 v30, v30
	s_nop 1
	v_add_f32_e32 v44, v30, v31
	v_sub_f32_e32 v31, v245, v2
	v_mul_f32_e32 v31, 0x3fb8aa3b, v31
	v_exp_f32_e32 v31, v31
	s_nop 1
	v_add_f32_e32 v45, v31, v44
	v_sub_f32_e32 v44, v244, v2
	v_mul_f32_e32 v44, 0x3fb8aa3b, v44
	v_exp_f32_e32 v44, v44
	s_nop 1
	v_add_f32_e32 v46, v44, v45
	v_sub_f32_e32 v45, v243, v2
	v_mul_f32_e32 v45, 0x3fb8aa3b, v45
	v_exp_f32_e32 v45, v45
	s_nop 1
	v_add_f32_e32 v47, v45, v46
	v_sub_f32_e32 v46, v241, v2
	v_mul_f32_e32 v46, 0x3fb8aa3b, v46
	v_exp_f32_e32 v46, v46
	s_nop 1
	v_add_f32_e32 v56, v46, v47
	v_sub_f32_e32 v47, v239, v2
	v_mul_f32_e32 v47, 0x3fb8aa3b, v47
	v_exp_f32_e32 v47, v47
	s_nop 1
	v_add_f32_e32 v59, v47, v56
	v_sub_f32_e32 v56, v145, v2
	v_mul_f32_e32 v56, 0x3fb8aa3b, v56
	v_exp_f32_e32 v56, v56
	s_nop 1
	v_add_f32_e32 v60, v56, v59
	v_sub_f32_e32 v59, v132, v2
	v_mul_f32_e32 v59, 0x3fb8aa3b, v59
	v_exp_f32_e32 v59, v59
	s_nop 1
	v_add_f32_e32 v63, v59, v60
	v_sub_f32_e32 v60, v127, v2
	v_mul_f32_e32 v60, 0x3fb8aa3b, v60
	v_exp_f32_e32 v60, v60
	s_nop 1
	v_add_f32_e32 v65, v60, v63
	v_sub_f32_e32 v63, v76, v2
	v_mul_f32_e32 v63, 0x3fb8aa3b, v63
	v_exp_f32_e32 v63, v63
	s_nop 1
	v_add_f32_e32 v69, v63, v65
	v_sub_f32_e32 v65, v68, v2
	v_mul_f32_e32 v65, 0x3fb8aa3b, v65
	v_sub_f32_e32 v68, v242, v2
	v_exp_f32_e32 v65, v65
	v_mul_f32_e32 v68, 0x3fb8aa3b, v68
	v_exp_f32_e32 v68, v68
	v_add_f32_e32 v69, v65, v69
	s_nop 0
	v_add_f32_e32 v72, v68, v69
; __device__ __forceinline__ float fexp(float x) { return __builtin_amdgcn_exp2f(x * 1.44269504089f); }
; __device__ __forceinline__ float shfl_xor_(float v, int m) { return __builtin_bit_cast(float, __builtin_amdgcn_ds_bpermute((lane_id() ^ m) << 2, __builtin_bit_cast(int, v))); }
; __device__ __forceinline__ void phase_attn(const Frame& F, const Args& a) {
;     ...
;         mx = fmaxf(mx, shfl_xor_(mx, 32));
;         float sum = 0.f;
; #pragma unroll
;         for (int kt = 0; kt < 5; ++kt)
; #pragma unroll
;             for (int e = 0; e < 16; ++e) { const float pv = (x[kt][e] > -1e29f) ? fexp(x[kt][e] - mx) : 0.f; x[kt][e] = pv; sum += pv; }
;         sum += shfl_xor_(sum, 32);
;         const float inv = 1.0f / sum;
;         if (hh == 0) { const size_t tok = (size_t)seq * SEQ + (size_t)(32 * qb + li) * d + p; LSE[((size_t)g * T + tok) * 4 + h] = mx + __builtin_amdgcn_logf(sum) * 0.69314718056f; }
	v_sub_f32_e32 v69, v240, v2
	v_mul_f32_e32 v69, 0x3fb8aa3b, v69
	v_exp_f32_e32 v69, v69
	s_nop 1
	v_add_f32_e32 v74, v69, v72
	v_sub_f32_e32 v72, v184, v2
	v_mul_f32_e32 v72, 0x3fb8aa3b, v72
	v_exp_f32_e32 v72, v72
	s_nop 1
	v_add_f32_e32 v76, v72, v74
	v_sub_f32_e32 v74, v135, v2
	v_mul_f32_e32 v74, 0x3fb8aa3b, v74
	v_exp_f32_e32 v74, v74
	s_nop 1
	v_add_f32_e32 v120, v74, v76
	v_sub_f32_e32 v76, v129, v2
	v_mul_f32_e32 v76, 0x3fb8aa3b, v76
	v_exp_f32_e32 v76, v76
	s_nop 1
	v_sub_f32_e32 v78, v78, v2
	v_mul_f32_e32 v78, 0x3fb8aa3b, v78
	v_exp_f32_e32 v78, v78
	v_add_f32_e32 v120, v76, v120
	v_add_f32_e32 v122, v78, v120
	v_sub_f32_e32 v120, v121, v2
	v_mul_f32_e32 v120, 0x3fb8aa3b, v120
	v_exp_f32_e32 v120, v120
	s_nop 1
	v_sub_f32_e32 v79, v79, v2
	v_mul_f32_e32 v79, 0x3fb8aa3b, v79
	v_exp_f32_e32 v79, v79
	v_add_f32_e32 v121, v120, v122
	v_mbcnt_lo_u32_b32 v122, -1, 0
	v_mbcnt_hi_u32_b32 v122, -1, v122
	v_sub_f32_e32 v77, v77, v2
	v_mul_f32_e32 v77, 0x3fb8aa3b, v77
	v_exp_f32_e32 v77, v77
	v_add_f32_e32 v121, v79, v121
	v_lshlrev_b32_e32 v122, 2, v122
	v_xor_b32_e32 v122, 0x80, v122
	v_sub_f32_e32 v75, v75, v2
	v_mul_f32_e32 v75, 0x3fb8aa3b, v75
	v_exp_f32_e32 v75, v75
	v_add_f32_e32 v121, v77, v121
	v_sub_f32_e32 v73, v73, v2
	v_mul_f32_e32 v73, 0x3fb8aa3b, v73
	v_exp_f32_e32 v73, v73
	v_add_f32_e32 v121, v75, v121
	v_sub_f32_e32 v71, v71, v2
	v_mul_f32_e32 v71, 0x3fb8aa3b, v71
	v_exp_f32_e32 v71, v71
	v_add_f32_e32 v121, v73, v121
	v_sub_f32_e32 v70, v70, v2
	v_mul_f32_e32 v70, 0x3fb8aa3b, v70
	v_exp_f32_e32 v70, v70
	v_add_f32_e32 v121, v71, v121
	v_sub_f32_e32 v67, v67, v2
	v_mul_f32_e32 v67, 0x3fb8aa3b, v67
	v_exp_f32_e32 v67, v67
	v_add_f32_e32 v121, v70, v121
	v_sub_f32_e32 v66, v66, v2
	v_mul_f32_e32 v66, 0x3fb8aa3b, v66
	v_exp_f32_e32 v66, v66
	v_add_f32_e32 v121, v67, v121
	v_sub_f32_e32 v64, v64, v2
	v_mul_f32_e32 v64, 0x3fb8aa3b, v64
	v_exp_f32_e32 v64, v64
	v_add_f32_e32 v121, v66, v121
	v_sub_f32_e32 v62, v62, v2
	v_mul_f32_e32 v62, 0x3fb8aa3b, v62
	v_exp_f32_e32 v62, v62
	v_add_f32_e32 v121, v64, v121
	v_sub_f32_e32 v61, v61, v2
	v_mul_f32_e32 v61, 0x3fb8aa3b, v61
	v_exp_f32_e32 v61, v61
	v_add_f32_e32 v121, v62, v121
	v_sub_f32_e32 v58, v58, v2
	v_mul_f32_e32 v58, 0x3fb8aa3b, v58
	v_exp_f32_e32 v58, v58
	v_add_f32_e32 v121, v61, v121
	v_sub_f32_e32 v57, v57, v2
	v_mul_f32_e32 v57, 0x3fb8aa3b, v57
	v_exp_f32_e32 v57, v57
	v_add_f32_e32 v121, v58, v121
	v_sub_f32_e32 v55, v55, v2
	v_mul_f32_e32 v55, 0x3fb8aa3b, v55
	v_exp_f32_e32 v55, v55
	v_add_f32_e32 v121, v57, v121
	v_sub_f32_e32 v54, v54, v2
	v_mul_f32_e32 v54, 0x3fb8aa3b, v54
	v_exp_f32_e32 v54, v54
	v_add_f32_e32 v121, v55, v121
	v_sub_f32_e32 v53, v53, v2
	v_mul_f32_e32 v53, 0x3fb8aa3b, v53
	v_exp_f32_e32 v53, v53
	v_add_f32_e32 v121, v54, v121
	v_sub_f32_e32 v52, v52, v2
	v_mul_f32_e32 v52, 0x3fb8aa3b, v52
	v_exp_f32_e32 v52, v52
	v_add_f32_e32 v121, v53, v121
	v_sub_f32_e32 v51, v51, v2
	v_mul_f32_e32 v51, 0x3fb8aa3b, v51
	v_exp_f32_e32 v51, v51
	v_add_f32_e32 v121, v52, v121
	v_sub_f32_e32 v50, v50, v2
	v_mul_f32_e32 v50, 0x3fb8aa3b, v50
	v_exp_f32_e32 v50, v50
	v_add_f32_e32 v121, v51, v121
	v_sub_f32_e32 v49, v49, v2
	v_mul_f32_e32 v49, 0x3fb8aa3b, v49
	v_exp_f32_e32 v49, v49
	v_add_f32_e32 v121, v50, v121
	v_sub_f32_e32 v48, v48, v2
	v_mul_f32_e32 v48, 0x3fb8aa3b, v48
	v_exp_f32_e32 v48, v48
	v_add_f32_e32 v121, v49, v121
	v_sub_f32_e32 v43, v43, v2
	v_mul_f32_e32 v43, 0x3fb8aa3b, v43
	v_exp_f32_e32 v43, v43
	v_add_f32_e32 v121, v48, v121
	v_sub_f32_e32 v42, v42, v2
	v_mul_f32_e32 v42, 0x3fb8aa3b, v42
	v_exp_f32_e32 v42, v42
	v_add_f32_e32 v121, v43, v121
	v_sub_f32_e32 v41, v41, v2
	v_mul_f32_e32 v41, 0x3fb8aa3b, v41
	v_exp_f32_e32 v41, v41
	v_add_f32_e32 v121, v42, v121
	v_sub_f32_e32 v40, v40, v2
	v_mul_f32_e32 v40, 0x3fb8aa3b, v40
	v_exp_f32_e32 v40, v40
	v_add_f32_e32 v121, v41, v121
	v_sub_f32_e32 v38, v38, v2
	v_mul_f32_e32 v38, 0x3fb8aa3b, v38
	v_exp_f32_e32 v38, v38
	v_add_f32_e32 v121, v40, v121
	v_sub_f32_e32 v39, v39, v2
	v_mul_f32_e32 v39, 0x3fb8aa3b, v39
	v_exp_f32_e32 v39, v39
	v_add_f32_e32 v121, v38, v121
	v_sub_f32_e32 v37, v37, v2
	v_mul_f32_e32 v37, 0x3fb8aa3b, v37
	v_exp_f32_e32 v37, v37
	v_add_f32_e32 v121, v39, v121
	v_sub_f32_e32 v36, v36, v2
	v_mul_f32_e32 v36, 0x3fb8aa3b, v36
	v_exp_f32_e32 v36, v36
	v_add_f32_e32 v121, v37, v121
	v_sub_f32_e32 v35, v35, v2
	v_mul_f32_e32 v35, 0x3fb8aa3b, v35
	v_exp_f32_e32 v35, v35
	v_add_f32_e32 v121, v36, v121
	v_sub_f32_e32 v34, v34, v2
	v_mul_f32_e32 v34, 0x3fb8aa3b, v34
	v_exp_f32_e32 v34, v34
	v_add_f32_e32 v121, v35, v121
	v_sub_f32_e32 v33, v33, v2
	v_mul_f32_e32 v33, 0x3fb8aa3b, v33
	v_exp_f32_e32 v33, v33
	v_add_f32_e32 v121, v34, v121
	v_sub_f32_e32 v32, v32, v2
	v_mul_f32_e32 v32, 0x3fb8aa3b, v32
	v_exp_f32_e32 v32, v32
	v_add_f32_e32 v121, v33, v121
	v_sub_f32_e32 v22, v22, v2
	v_mul_f32_e32 v22, 0x3fb8aa3b, v22
	v_exp_f32_e32 v22, v22
	v_add_f32_e32 v121, v32, v121
	v_sub_f32_e32 v20, v20, v2
	v_mul_f32_e32 v20, 0x3fb8aa3b, v20
	v_exp_f32_e32 v20, v20
	v_add_f32_e32 v121, v22, v121
	v_sub_f32_e32 v19, v19, v2
	v_mul_f32_e32 v19, 0x3fb8aa3b, v19
	v_exp_f32_e32 v19, v19
	v_add_f32_e32 v121, v20, v121
	v_sub_f32_e32 v18, v18, v2
	v_mul_f32_e32 v18, 0x3fb8aa3b, v18
	v_exp_f32_e32 v18, v18
	v_add_f32_e32 v121, v19, v121
	v_sub_f32_e32 v16, v16, v2
	v_mul_f32_e32 v16, 0x3fb8aa3b, v16
	v_exp_f32_e32 v16, v16
	v_add_f32_e32 v121, v18, v121
	v_sub_f32_e32 v15, v15, v2
	v_mul_f32_e32 v15, 0x3fb8aa3b, v15
	v_exp_f32_e32 v15, v15
	v_add_f32_e32 v121, v16, v121
	v_sub_f32_e32 v13, v13, v2
	v_mul_f32_e32 v13, 0x3fb8aa3b, v13
	v_exp_f32_e32 v13, v13
	v_add_f32_e32 v121, v15, v121
	v_sub_f32_e32 v12, v12, v2
	v_mul_f32_e32 v12, 0x3fb8aa3b, v12
	v_exp_f32_e32 v12, v12
	v_add_f32_e32 v121, v13, v121
	v_sub_f32_e32 v21, v21, v2
	v_mul_f32_e32 v21, 0x3fb8aa3b, v21
	v_exp_f32_e32 v21, v21
	v_add_f32_e32 v121, v12, v121
	v_add_f32_e32 v121, v21, v121
	ds_bpermute_b32 v122, v122, v121
	s_mov_b64 s[26:27], exec
	v_readlane_b32 s30, v255, 11
	v_readlane_b32 s31, v255, 12
	s_and_b64 s[30:31], s[26:27], s[30:31]
	s_xor_b64 s[26:27], s[30:31], s[26:27]
	s_mov_b64 exec, s[30:31]
	s_add_u32 s28, s9, s14
	s_addc_u32 s29, s8, s15
	s_or_b64 s[28:29], s[28:29], s[82:83]
	s_or_saveexec_b64 s[26:27], s[26:27]
	s_waitcnt lgkmcnt(0)
	v_add_f32_e32 v121, v121, v122
	v_mov_b64_e32 v[144:145], s[28:29]
	s_xor_b64 exec, exec, s[26:27]
	s_cbranch_execz .LBB0_1004
	v_log_f32_e32 v122, v121
	s_add_u32 s14, s9, s14
	v_or_b32_e32 v123, s5, v141
	s_addc_u32 s15, s8, s15
	v_lshlrev_b32_e32 v184, s4, v123
	s_or_b64 s[8:9], s[14:15], s[82:83]
	v_readlane_b32 s14, v255, 27
	v_fmac_f32_e32 v2, 0x3f317218, v122
	v_lshl_add_u64 v[122:123], s[8:9], 0, v[184:185]
	v_readlane_b32 s15, v255, 28
	s_lshl_b32 s82, s7, 2
	v_mov_b64_e32 v[144:145], s[8:9]
	v_lshl_add_u64 v[122:123], v[122:123], 4, s[14:15]
	v_lshl_add_u64 v[122:123], v[122:123], 0, s[82:83]
	global_store_dword v[122:123], v2, off
	s_branch .LBB0_1004
